# MLA up-projection GEMM tile epilogue: 32 predicated dwordx2 stores per lane replaced by 16 dwordx4 (permlane16 row swaps), wave-uniform range test
# speedup vs baseline: 1.1216x; 1.0065x over previous
.LBB0_516:
	s_bitcmp1_b32 s19, 0
	s_cselect_b32 s2, 0x10400, 0
	v_or_b32_e32 v2, s2, v176
	v_add3_u32 v148, v2, v171, v169
	v_add3_u32 v2, v2, v170, v169
	ds_read_b128 v[132:135], v148 offset:33792
	ds_read_b128 v[136:139], v2
	ds_read_b128 v[140:143], v148 offset:35840
	ds_read_b128 v[144:147], v148 offset:37888
	ds_read_b128 v[148:151], v148 offset:39936
	v_lshrrev_b32_e32 v156, 2, v164
	s_waitcnt lgkmcnt(3)
	v_mfma_f32_16x16x32_bf16 v[128:131], v[132:135], v[136:139], v[128:131]
	s_waitcnt lgkmcnt(2)
	v_mfma_f32_16x16x32_bf16 v[124:127], v[140:143], v[136:139], v[124:127]
	s_waitcnt lgkmcnt(1)
	v_mfma_f32_16x16x32_bf16 v[120:123], v[144:147], v[136:139], v[120:123]
	s_waitcnt lgkmcnt(0)
	v_mfma_f32_16x16x32_bf16 v[116:119], v[148:151], v[136:139], v[116:119]
	ds_read_b128 v[136:139], v2 offset:2048
	s_waitcnt lgkmcnt(0)
	v_mfma_f32_16x16x32_bf16 v[112:115], v[132:135], v[136:139], v[112:115]
	v_mfma_f32_16x16x32_bf16 v[108:111], v[140:143], v[136:139], v[108:111]
	v_mfma_f32_16x16x32_bf16 v[104:107], v[144:147], v[136:139], v[104:107]
	v_mfma_f32_16x16x32_bf16 v[100:103], v[148:151], v[136:139], v[100:103]
	ds_read_b128 v[136:139], v2 offset:4096
	s_waitcnt lgkmcnt(0)
	v_mfma_f32_16x16x32_bf16 v[96:99], v[132:135], v[136:139], v[96:99]
	v_mfma_f32_16x16x32_bf16 v[92:95], v[140:143], v[136:139], v[92:95]
	v_mfma_f32_16x16x32_bf16 v[88:91], v[144:147], v[136:139], v[88:91]
	v_mfma_f32_16x16x32_bf16 v[84:87], v[148:151], v[136:139], v[84:87]
	ds_read_b128 v[136:139], v2 offset:6144
	s_waitcnt lgkmcnt(0)
	v_mfma_f32_16x16x32_bf16 v[80:83], v[132:135], v[136:139], v[80:83]
	v_mfma_f32_16x16x32_bf16 v[76:79], v[140:143], v[136:139], v[76:79]
	v_mfma_f32_16x16x32_bf16 v[72:75], v[144:147], v[136:139], v[72:75]
	v_mfma_f32_16x16x32_bf16 v[68:71], v[148:151], v[136:139], v[68:71]
	ds_read_b128 v[136:139], v2 offset:8192
	s_waitcnt lgkmcnt(0)
	v_mfma_f32_16x16x32_bf16 v[64:67], v[132:135], v[136:139], v[64:67]
	v_mfma_f32_16x16x32_bf16 v[60:63], v[140:143], v[136:139], v[60:63]
	v_mfma_f32_16x16x32_bf16 v[56:59], v[144:147], v[136:139], v[56:59]
	v_mfma_f32_16x16x32_bf16 v[52:55], v[148:151], v[136:139], v[52:55]
	ds_read_b128 v[136:139], v2 offset:10240
	s_waitcnt lgkmcnt(0)
	v_mfma_f32_16x16x32_bf16 v[48:51], v[132:135], v[136:139], v[48:51]
	v_mfma_f32_16x16x32_bf16 v[44:47], v[140:143], v[136:139], v[44:47]
	v_mfma_f32_16x16x32_bf16 v[40:43], v[144:147], v[136:139], v[40:43]
	v_mfma_f32_16x16x32_bf16 v[36:39], v[148:151], v[136:139], v[36:39]
	ds_read_b128 v[136:139], v2 offset:12288
	s_waitcnt lgkmcnt(0)
	v_mfma_f32_16x16x32_bf16 v[32:35], v[132:135], v[136:139], v[32:35]
	v_mfma_f32_16x16x32_bf16 v[28:31], v[140:143], v[136:139], v[28:31]
	v_mfma_f32_16x16x32_bf16 v[24:27], v[144:147], v[136:139], v[24:27]
	v_mfma_f32_16x16x32_bf16 v[20:23], v[148:151], v[136:139], v[20:23]
	ds_read_b128 v[136:139], v2 offset:14336
	v_or_b32_e32 v2, s2, v172
	v_add3_u32 v152, v2, v171, v169
	v_add3_u32 v2, v2, v170, v169
	s_waitcnt lgkmcnt(0)
	v_mfma_f32_16x16x32_bf16 v[16:19], v[132:135], v[136:139], v[16:19]
	ds_read_b128 v[132:135], v152 offset:33792
	v_mfma_f32_16x16x32_bf16 v[12:15], v[140:143], v[136:139], v[12:15]
	v_mfma_f32_16x16x32_bf16 v[8:11], v[144:147], v[136:139], v[8:11]
	v_mfma_f32_16x16x32_bf16 v[4:7], v[148:151], v[136:139], v[4:7]
	ds_read_b128 v[136:139], v152 offset:35840
	ds_read_b128 v[140:143], v2
	ds_read_b128 v[144:147], v2 offset:2048
	ds_read_b128 v[148:151], v152 offset:37888
	ds_read_b128 v[152:155], v152 offset:39936
	s_waitcnt lgkmcnt(3)
	v_mfma_f32_16x16x32_bf16 v[128:131], v[132:135], v[140:143], v[128:131]
	v_mfma_f32_16x16x32_bf16 v[124:127], v[136:139], v[140:143], v[124:127]
	s_waitcnt lgkmcnt(1)
	v_mfma_f32_16x16x32_bf16 v[120:123], v[148:151], v[140:143], v[120:123]
	s_waitcnt lgkmcnt(0)
	v_mfma_f32_16x16x32_bf16 v[116:119], v[152:155], v[140:143], v[116:119]
	v_mfma_f32_16x16x32_bf16 v[112:115], v[132:135], v[144:147], v[112:115]
	v_mfma_f32_16x16x32_bf16 v[108:111], v[136:139], v[144:147], v[108:111]
	v_mfma_f32_16x16x32_bf16 v[104:107], v[148:151], v[144:147], v[104:107]
	v_mfma_f32_16x16x32_bf16 v[100:103], v[152:155], v[144:147], v[100:103]
	ds_read_b128 v[140:143], v2 offset:4096
	ds_read_b128 v[144:147], v2 offset:6144
	s_waitcnt lgkmcnt(1)
	v_mfma_f32_16x16x32_bf16 v[96:99], v[132:135], v[140:143], v[96:99]
	v_mfma_f32_16x16x32_bf16 v[92:95], v[136:139], v[140:143], v[92:95]
	v_mfma_f32_16x16x32_bf16 v[88:91], v[148:151], v[140:143], v[88:91]
	v_mfma_f32_16x16x32_bf16 v[84:87], v[152:155], v[140:143], v[84:87]
	s_waitcnt lgkmcnt(0)
	v_mfma_f32_16x16x32_bf16 v[80:83], v[132:135], v[144:147], v[80:83]
	v_mfma_f32_16x16x32_bf16 v[76:79], v[136:139], v[144:147], v[76:79]
	v_mfma_f32_16x16x32_bf16 v[72:75], v[148:151], v[144:147], v[72:75]
	v_mfma_f32_16x16x32_bf16 v[68:71], v[152:155], v[144:147], v[68:71]
	ds_read_b128 v[140:143], v2 offset:8192
	ds_read_b128 v[144:147], v2 offset:10240
	s_waitcnt lgkmcnt(1)
	v_mfma_f32_16x16x32_bf16 v[64:67], v[132:135], v[140:143], v[64:67]
	v_mfma_f32_16x16x32_bf16 v[60:63], v[136:139], v[140:143], v[60:63]
	v_mfma_f32_16x16x32_bf16 v[56:59], v[148:151], v[140:143], v[56:59]
	v_mfma_f32_16x16x32_bf16 v[52:55], v[152:155], v[140:143], v[52:55]
	s_waitcnt lgkmcnt(0)
	v_mfma_f32_16x16x32_bf16 v[48:51], v[132:135], v[144:147], v[48:51]
	v_mfma_f32_16x16x32_bf16 v[44:47], v[136:139], v[144:147], v[44:47]
	v_mfma_f32_16x16x32_bf16 v[40:43], v[148:151], v[144:147], v[40:43]
	v_mfma_f32_16x16x32_bf16 v[36:39], v[152:155], v[144:147], v[36:39]
	ds_read_b128 v[140:143], v2 offset:12288
	ds_read_b128 v[144:147], v2 offset:14336
	v_lshlrev_b32_e32 v2, 6, v166
	s_waitcnt lgkmcnt(0)
	v_mfma_f32_16x16x32_bf16 v[32:35], v[132:135], v[140:143], v[32:35]
	s_barrier
	v_mfma_f32_16x16x32_bf16 v[28:31], v[136:139], v[140:143], v[28:31]
	v_mfma_f32_16x16x32_bf16 v[24:27], v[148:151], v[140:143], v[24:27]
	v_mfma_f32_16x16x32_bf16 v[20:23], v[152:155], v[140:143], v[20:23]
	v_and_b32_e32 v140, 12, v156
	v_add3_u32 v2, v140, s16, v2
	v_lshlrev_b32_e32 v140, 7, v165
	v_mfma_f32_16x16x32_bf16 v[16:19], v[132:135], v[144:147], v[16:19]
	v_and_b32_e32 v132, 15, v164
	v_add3_u32 v134, v132, s17, v140
	v_mad_u64_u32 v[132:133], s[2:3], v134, s18, 0
	v_ashrrev_i32_e32 v135, 31, v134
	v_mfma_f32_16x16x32_bf16 v[12:15], v[136:139], v[144:147], v[12:15]
	v_mov_b32_e32 v136, v133
	v_mad_u64_u32 v[136:137], s[2:3], v135, s18, v[136:137]
	v_mfma_f32_16x16x32_bf16 v[8:11], v[148:151], v[144:147], v[8:11]
	v_mov_b32_e32 v133, v136
	v_lshl_add_u64 v[132:133], v[132:133], 1, s[14:15]
	v_cmp_gt_u32_e32 vcc, s18, v2
	v_mfma_f32_16x16x32_bf16 v[4:7], v[152:155], v[144:147], v[4:7]
	s_cbranch_vccz .Lmla_st_done
	v_lshl_add_u64 v[132:133], v[2:3], 1, v[132:133]
	v_and_b32_e32 v140, 16, v164
	v_lshrrev_b32_e32 v141, 1, v140
	v_add_u32_e32 v140, v140, v141
	v_mov_b32_e32 v141, 0
	s_lshl_b32 s4, s18, 5
	s_mov_b32 s5, 0
	v_lshl_add_u64 v[132:133], v[140:141], 0, v[132:133]
	v_cvt_pk_bf16_f32 v127, v126, v127
	v_cvt_pk_bf16_f32 v126, v124, v125
	v_cvt_pk_bf16_f32 v124, v128, v129
	v_cvt_pk_bf16_f32 v125, v130, v131
	v_cvt_pk_bf16_f32 v119, v118, v119
	v_cvt_pk_bf16_f32 v118, v116, v117
	v_cvt_pk_bf16_f32 v116, v120, v121
	v_cvt_pk_bf16_f32 v117, v122, v123
	s_nop 1
	v_permlane16_swap_b32 v124, v126
	v_permlane16_swap_b32 v125, v127
	v_permlane16_swap_b32 v116, v118
	v_permlane16_swap_b32 v117, v119
	s_nop 1
	global_store_dwordx4 v[132:133], v[124:127], off
	global_store_dwordx4 v[132:133], v[116:119], off offset:64
	v_lshl_add_u64 v[132:133], s[4:5], 0, v[132:133]
	v_cvt_pk_bf16_f32 v111, v110, v111
	v_cvt_pk_bf16_f32 v110, v108, v109
	v_cvt_pk_bf16_f32 v108, v112, v113
	v_cvt_pk_bf16_f32 v109, v114, v115
	v_cvt_pk_bf16_f32 v103, v102, v103
	v_cvt_pk_bf16_f32 v102, v100, v101
	v_cvt_pk_bf16_f32 v100, v104, v105
	v_cvt_pk_bf16_f32 v101, v106, v107
	s_nop 1
	v_permlane16_swap_b32 v108, v110
	v_permlane16_swap_b32 v109, v111
	v_permlane16_swap_b32 v100, v102
	v_permlane16_swap_b32 v101, v103
	s_nop 1
	global_store_dwordx4 v[132:133], v[108:111], off
	global_store_dwordx4 v[132:133], v[100:103], off offset:64
	v_lshl_add_u64 v[132:133], s[4:5], 0, v[132:133]
	v_cvt_pk_bf16_f32 v95, v94, v95
	v_cvt_pk_bf16_f32 v94, v92, v93
	v_cvt_pk_bf16_f32 v92, v96, v97
	v_cvt_pk_bf16_f32 v93, v98, v99
	v_cvt_pk_bf16_f32 v87, v86, v87
	v_cvt_pk_bf16_f32 v86, v84, v85
	v_cvt_pk_bf16_f32 v84, v88, v89
	v_cvt_pk_bf16_f32 v85, v90, v91
	s_nop 1
	v_permlane16_swap_b32 v92, v94
	v_permlane16_swap_b32 v93, v95
	v_permlane16_swap_b32 v84, v86
	v_permlane16_swap_b32 v85, v87
	s_nop 1
	global_store_dwordx4 v[132:133], v[92:95], off
	global_store_dwordx4 v[132:133], v[84:87], off offset:64
	v_lshl_add_u64 v[132:133], s[4:5], 0, v[132:133]
	v_cvt_pk_bf16_f32 v79, v78, v79
	v_cvt_pk_bf16_f32 v78, v76, v77
	v_cvt_pk_bf16_f32 v76, v80, v81
	v_cvt_pk_bf16_f32 v77, v82, v83
	v_cvt_pk_bf16_f32 v71, v70, v71
	v_cvt_pk_bf16_f32 v70, v68, v69
	v_cvt_pk_bf16_f32 v68, v72, v73
	v_cvt_pk_bf16_f32 v69, v74, v75
	s_nop 1
	v_permlane16_swap_b32 v76, v78
	v_permlane16_swap_b32 v77, v79
	v_permlane16_swap_b32 v68, v70
	v_permlane16_swap_b32 v69, v71
	s_nop 1
	global_store_dwordx4 v[132:133], v[76:79], off
	global_store_dwordx4 v[132:133], v[68:71], off offset:64
	v_lshl_add_u64 v[132:133], s[4:5], 0, v[132:133]
	v_cvt_pk_bf16_f32 v63, v62, v63
	v_cvt_pk_bf16_f32 v62, v60, v61
	v_cvt_pk_bf16_f32 v60, v64, v65
	v_cvt_pk_bf16_f32 v61, v66, v67
	v_cvt_pk_bf16_f32 v55, v54, v55
	v_cvt_pk_bf16_f32 v54, v52, v53
	v_cvt_pk_bf16_f32 v52, v56, v57
	v_cvt_pk_bf16_f32 v53, v58, v59
	s_nop 1
	v_permlane16_swap_b32 v60, v62
	v_permlane16_swap_b32 v61, v63
	v_permlane16_swap_b32 v52, v54
	v_permlane16_swap_b32 v53, v55
	s_nop 1
	global_store_dwordx4 v[132:133], v[60:63], off
	global_store_dwordx4 v[132:133], v[52:55], off offset:64
	v_lshl_add_u64 v[132:133], s[4:5], 0, v[132:133]
	v_cvt_pk_bf16_f32 v47, v46, v47
	v_cvt_pk_bf16_f32 v46, v44, v45
	v_cvt_pk_bf16_f32 v44, v48, v49
	v_cvt_pk_bf16_f32 v45, v50, v51
	v_cvt_pk_bf16_f32 v39, v38, v39
	v_cvt_pk_bf16_f32 v38, v36, v37
	v_cvt_pk_bf16_f32 v36, v40, v41
	v_cvt_pk_bf16_f32 v37, v42, v43
	s_nop 1
	v_permlane16_swap_b32 v44, v46
	v_permlane16_swap_b32 v45, v47
	v_permlane16_swap_b32 v36, v38
	v_permlane16_swap_b32 v37, v39
	s_nop 1
	global_store_dwordx4 v[132:133], v[44:47], off
	global_store_dwordx4 v[132:133], v[36:39], off offset:64
	v_lshl_add_u64 v[132:133], s[4:5], 0, v[132:133]
	v_cvt_pk_bf16_f32 v31, v30, v31
	v_cvt_pk_bf16_f32 v30, v28, v29
	v_cvt_pk_bf16_f32 v28, v32, v33
	v_cvt_pk_bf16_f32 v29, v34, v35
	v_cvt_pk_bf16_f32 v23, v22, v23
	v_cvt_pk_bf16_f32 v22, v20, v21
	v_cvt_pk_bf16_f32 v20, v24, v25
	v_cvt_pk_bf16_f32 v21, v26, v27
	s_nop 1
	v_permlane16_swap_b32 v28, v30
	v_permlane16_swap_b32 v29, v31
	v_permlane16_swap_b32 v20, v22
	v_permlane16_swap_b32 v21, v23
	s_nop 1
	global_store_dwordx4 v[132:133], v[28:31], off
	global_store_dwordx4 v[132:133], v[20:23], off offset:64
	v_lshl_add_u64 v[132:133], s[4:5], 0, v[132:133]
	v_cvt_pk_bf16_f32 v15, v14, v15
	v_cvt_pk_bf16_f32 v14, v12, v13
	v_cvt_pk_bf16_f32 v12, v16, v17
	v_cvt_pk_bf16_f32 v13, v18, v19
	v_cvt_pk_bf16_f32 v7, v6, v7
	v_cvt_pk_bf16_f32 v6, v4, v5
	v_cvt_pk_bf16_f32 v4, v8, v9
	v_cvt_pk_bf16_f32 v5, v10, v11
	s_nop 1
	v_permlane16_swap_b32 v12, v14
	v_permlane16_swap_b32 v13, v15
	v_permlane16_swap_b32 v4, v6
	v_permlane16_swap_b32 v5, v7
	s_nop 1
	global_store_dwordx4 v[132:133], v[12:15], off
	global_store_dwordx4 v[132:133], v[4:7], off offset:64
.Lmla_st_done:
	s_mov_b64 s[2:3], exec
	s_branch .LBB0_498
